# attention K/V LDS-DMAs use the default cache policy instead of nt: with the item table several workgroups of an XCD stream the same head's K/V at different times
# speedup vs baseline: 1.0055x; 1.0055x over previous
.Lpf_do:
	s_mul_i32 s0, s74, 6
	s_lshr_b32 s0, s100, s0
	s_and_b32 s1, s0, 7
	s_bfe_u32 s36, s0, 0x30003
	s_lshl_b32 s1, s1, 8
	s_lshr_b32 s0, s87, 6
	s_lshl_b32 s37, s36, 8
	s_add_i32 s0, s0, s37
	v_or_b32_e32 v148, s0, v209
	v_add_u32_e32 v148, s46, v148
	v_lshlrev_b32_e32 v148, 11, v148
	v_add_u32_e32 v148, s1, v148
	v_add_co_u32_e32 v132, vcc, v178, v148
	s_lshl_b32 s0, s87, 2
	v_addc_co_u32_e32 v133, vcc, 0, v179, vcc
	s_add_i32 s0, s0, 0x18000
	s_mov_b32 m0, s0
	s_nop 0
	global_load_lds_dwordx4 v[132:133], off
	s_add_i32 m0, s0, 992
	s_nop 0
	global_load_lds_dwordx4 v[132:133], off offset:32
	s_add_i32 m0, s0, 1984
	s_nop 0
	global_load_lds_dwordx4 v[132:133], off offset:64
	s_add_i32 m0, s0, 2976
	s_nop 0
	global_load_lds_dwordx4 v[132:133], off offset:96
	s_add_i32 m0, s0, 3968
	s_nop 0
	global_load_lds_dwordx4 v[132:133], off offset:128
	s_add_i32 m0, s0, 4960
	s_nop 0
	global_load_lds_dwordx4 v[132:133], off offset:160
	s_add_i32 m0, s0, 5952
	s_nop 0
	global_load_lds_dwordx4 v[132:133], off offset:192
	s_add_i32 m0, s0, 6944
	s_nop 0
	global_load_lds_dwordx4 v[132:133], off offset:224
	s_lshl_b32 s0, s46, 11
	s_add_i32 s1, s1, s0
	s_lshl_b32 s0, s36, 2
	s_or_b32 s0, s0, 3
	s_lshl_b32 s0, s0, 17
	s_add_i32 s0, s0, s1
	s_add_u32 s40, s42, s0
	s_addc_u32 s41, s43, 0
	s_add_u32 s66, s54, s0
	s_addc_u32 s67, s55, 0
	s_lshl_b32 s0, s36, 19
	s_or_b32 s0, s0, 0x40000
	s_add_i32 s36, s0, s1
	s_add_u32 s0, s42, s36
	s_addc_u32 s1, s43, 0
	s_add_u32 s36, s54, s36
	s_addc_u32 s37, s55, 0
	s_mov_b32 m0, s88
	s_nop 0
	global_load_lds_dwordx4 v176, s[40:41]
	s_mov_b32 m0, s89
	s_nop 0
	global_load_lds_dwordx4 v190, s[66:67]
	s_mov_b32 m0, s91
	s_nop 0
	global_load_lds_dwordx4 v192, s[40:41]
	s_mov_b32 m0, s92
	s_nop 0
	global_load_lds_dwordx4 v194, s[66:67]
	s_mov_b32 m0, s93
	s_nop 0
	global_load_lds_dwordx4 v176, s[0:1]
	s_mov_b32 m0, s94
	s_nop 0
	global_load_lds_dwordx4 v190, s[36:37]
	s_mov_b32 m0, s95
	s_nop 0
	global_load_lds_dwordx4 v192, s[0:1]
	s_mov_b32 m0, s96
	s_nop 0
	global_load_lds_dwordx4 v194, s[36:37]

.Lpf_q1:
	s_lshl_b32 s37, s0, 13
	v_add_u32_e32 v189, s37, v211
	s_lshl_b32 s37, s0, 3
	v_or_b32_e32 v16, s37, v212
	v_bitop3_b32 v17, s37, v207, v212 bitop3:0x36
	s_lshr_b32 s1, s1, 5
	v_lshlrev_b32_e32 v16, 11, v16
	v_lshlrev_b32_e32 v17, 4, v17
	s_and_b32 s1, s1, 2
	v_and_or_b32 v176, v17, s70, v16
	v_bitop3_b32 v17, s1, v213, v214 bitop3:0x36
	s_or_b32 s1, s37, 4
	s_lshl_b32 s83, s36, 2
	v_lshl_or_b32 v190, v17, 4, v16
	v_or_b32_e32 v16, s1, v212
	v_bitop3_b32 v17, s1, v207, v212 bitop3:0x36
	s_lshl_b32 s38, s36, 3
	v_lshlrev_b32_e32 v16, 11, v16
	v_lshlrev_b32_e32 v17, 4, v17
	s_bfe_u32 s1, s1, 0x20002
	s_or_b32 s86, s83, 3
	v_and_or_b32 v192, v17, s70, v16
	v_bitop3_b32 v17, s1, v213, v214 bitop3:0x36
	s_add_i32 s84, s0, s38
	s_add_i32 s85, s83, 4
	s_lshl_b32 s1, s86, 17
	s_add_u32 s40, s76, s1
	s_addc_u32 s41, s77, 0
	s_add_u32 s66, s81, s1
	s_addc_u32 s67, s82, 0
	s_lshl_b32 s87, s0, 11
	s_add_i32 s88, s87, 0
	s_lshl_b32 s0, s36, 19
	s_add_i32 s89, s88, 0xc000
	s_or_b32 s90, s87, 0x400
	s_add_i32 s91, s88, 0x400
	s_add_i32 s92, s88, 0xc400
	s_or_b32 s36, s0, 0x40000
	s_mov_b32 m0, s88
	s_add_u32 s0, s76, s36
	s_addc_u32 s1, s77, 0
	s_add_u32 s36, s81, s36
	v_lshl_or_b32 v194, v17, 4, v16
	s_addc_u32 s37, s82, 0
	s_add_i32 s93, s88, 0x4000
	s_add_i32 s94, s71, s87
	s_add_i32 s95, s88, 0x4400
	s_add_i32 s96, s71, s90
	v_mov_b32_e32 v185, v184
	v_mov_b32_e32 v96, v177
	v_mov_b32_e32 v97, v177
	v_mov_b32_e32 v110, v177
	v_mov_b32_e32 v111, v177
	v_mov_b32_e32 v98, v177
	v_mov_b32_e32 v99, v177
	v_mov_b32_e32 v100, v177
	v_mov_b32_e32 v101, v177
	v_mov_b32_e32 v102, v177
	v_mov_b32_e32 v103, v177
	v_mov_b32_e32 v104, v177
	v_mov_b32_e32 v105, v177
	v_mov_b32_e32 v106, v177
	v_mov_b32_e32 v107, v177
	v_mov_b32_e32 v108, v177
	v_mov_b32_e32 v109, v177
	v_mov_b64_e32 v[64:65], v[96:97]
	v_mov_b64_e32 v[80:81], v[96:97]
	v_mov_b64_e32 v[32:33], v[96:97]
	v_mov_b64_e32 v[48:49], v[96:97]
	v_mov_b64_e32 v[126:127], v[110:111]
	v_mov_b32_e32 v191, v177
	v_mov_b32_e32 v193, v177
	v_mov_b32_e32 v195, v177
	s_sub_i32 s97, s79, 64
	s_add_i32 s65, s79, 0xffffffa0
	s_or_b32 s38, s38, 6
	s_add_i32 s39, s79, 0xffffff80
	v_mov_b32_e32 v196, v177
	v_mov_b32_e32 v197, v177
	v_mov_b32_e32 v199, 0xf149f2ca
	v_mov_b32_e32 v201, 0xf149f2ca
	v_mov_b64_e32 v[66:67], v[98:99]
	v_mov_b64_e32 v[68:69], v[100:101]
	v_mov_b64_e32 v[70:71], v[102:103]
	v_mov_b64_e32 v[72:73], v[104:105]
	v_mov_b64_e32 v[74:75], v[106:107]
	v_mov_b64_e32 v[76:77], v[108:109]
	v_mov_b64_e32 v[78:79], v[110:111]
	v_mov_b64_e32 v[82:83], v[98:99]
	v_mov_b64_e32 v[84:85], v[100:101]
	v_mov_b64_e32 v[86:87], v[102:103]
	v_mov_b64_e32 v[88:89], v[104:105]
	v_mov_b64_e32 v[90:91], v[106:107]
	v_mov_b64_e32 v[92:93], v[108:109]
	v_mov_b64_e32 v[94:95], v[110:111]
	v_mov_b64_e32 v[34:35], v[98:99]
	v_mov_b64_e32 v[36:37], v[100:101]
	v_mov_b64_e32 v[38:39], v[102:103]
	v_mov_b64_e32 v[40:41], v[104:105]
	v_mov_b64_e32 v[42:43], v[106:107]
	v_mov_b64_e32 v[44:45], v[108:109]
	v_mov_b64_e32 v[46:47], v[110:111]
	v_mov_b64_e32 v[50:51], v[98:99]
	v_mov_b64_e32 v[52:53], v[100:101]
	v_mov_b64_e32 v[54:55], v[102:103]
	v_mov_b64_e32 v[56:57], v[104:105]
	v_mov_b64_e32 v[58:59], v[106:107]
	v_mov_b64_e32 v[60:61], v[108:109]
	v_mov_b64_e32 v[62:63], v[110:111]
	v_mov_b64_e32 v[124:125], v[108:109]
	v_mov_b64_e32 v[122:123], v[106:107]
	v_mov_b64_e32 v[120:121], v[104:105]
	v_mov_b64_e32 v[118:119], v[102:103]
	v_mov_b64_e32 v[116:117], v[100:101]
	v_mov_b64_e32 v[114:115], v[98:99]
	v_mov_b64_e32 v[112:113], v[96:97]
	v_mov_b32_e32 v0, v210
	s_cmp_lg_u32 s74, 0
	s_cbranch_scc1 .Lpf_q2
	s_mov_b32 m0, s88
	s_nop 0
	global_load_lds_dwordx4 v176, s[40:41]
	s_mov_b32 m0, s89
	s_nop 0
	global_load_lds_dwordx4 v190, s[66:67]
	s_mov_b32 m0, s91
	s_nop 0
	global_load_lds_dwordx4 v192, s[40:41]
	s_mov_b32 m0, s92
	s_nop 0
	global_load_lds_dwordx4 v194, s[66:67]
	s_mov_b32 m0, s93
	s_nop 0
	global_load_lds_dwordx4 v176, s[0:1]
	s_mov_b32 m0, s94
	s_nop 0
	global_load_lds_dwordx4 v190, s[36:37]
	s_mov_b32 m0, s95
	s_nop 0
	global_load_lds_dwordx4 v192, s[0:1]
	s_mov_b32 m0, s96
	s_nop 0
	global_load_lds_dwordx4 v194, s[36:37]
	s_waitcnt vmcnt(8)
	ds_write_b128 v189, v[144:147]
	ds_write_b128 v189, v[148:151] offset:1024
	ds_write_b128 v189, v[152:155] offset:2048
	ds_write_b128 v189, v[156:159] offset:3072
	ds_write_b128 v189, v[160:163] offset:4096
	ds_write_b128 v189, v[164:167] offset:5120
	ds_write_b128 v189, v[168:171] offset:6144
	ds_write_b128 v189, v[172:175] offset:7168

.LBB0_762:
	s_add_i32 s0, s37, 2
	s_lshl_b32 s0, s0, 17
	s_add_i32 s78, s0, 0xfffc0000
	s_add_u32 s0, s76, s78
	s_addc_u32 s1, s77, 0
	s_add_u32 s98, s81, s78
	s_addc_u32 s99, s82, 0
	s_add_i32 m0, s88, 0x8000
	s_nop 0
	global_load_lds_dwordx4 v176, s[0:1]
	s_add_i32 m0, s72, s87
	s_nop 0
	global_load_lds_dwordx4 v190, s[98:99]
	s_add_i32 m0, s88, 0x8400
	s_nop 0
	global_load_lds_dwordx4 v192, s[0:1]
	s_add_i32 m0, s72, s90
	s_nop 0
	global_load_lds_dwordx4 v194, s[98:99]
	s_cmp_ge_i32 s38, s84
	s_cbranch_scc1 .LBB0_758

.LBB0_786:
	s_add_i32 s0, s37, 1
	s_lshl_b32 s0, s0, 17
	s_add_i32 s78, s0, 0xfffc0000
	s_add_u32 s0, s76, s78
	s_addc_u32 s1, s77, 0
	s_add_u32 s98, s81, s78
	s_mov_b32 m0, s88
	s_addc_u32 s99, s82, 0
	global_load_lds_dwordx4 v176, s[0:1]
	s_mov_b32 m0, s89
	s_nop 0
	global_load_lds_dwordx4 v190, s[98:99]
	s_mov_b32 m0, s91
	s_nop 0
	global_load_lds_dwordx4 v192, s[0:1]
	s_mov_b32 m0, s92
	s_nop 0
	global_load_lds_dwordx4 v194, s[98:99]
	s_add_i32 s78, s38, -2
	s_cmp_ge_i32 s78, s84
	s_cbranch_scc1 .LBB0_777

.LBB0_799:
	s_lshl_b32 s0, s37, 17
	s_add_i32 s78, s0, 0xfffc0000
	s_add_u32 s0, s76, s78
	s_addc_u32 s1, s77, 0
	s_add_u32 s98, s81, s78
	s_mov_b32 m0, s93
	s_addc_u32 s99, s82, 0
	global_load_lds_dwordx4 v176, s[0:1]
	s_mov_b32 m0, s94
	s_nop 0
	global_load_lds_dwordx4 v190, s[98:99]
	s_mov_b32 m0, s95
	s_nop 0
	global_load_lds_dwordx4 v192, s[0:1]
	s_mov_b32 m0, s96
	s_nop 0
	global_load_lds_dwordx4 v194, s[98:99]
	s_add_i32 s78, s38, -4
	s_cmp_ge_i32 s78, s84
	s_cbranch_scc1 .LBB0_783
